# V10 + NSA tile loops staggered: waves 4-7 pre-read V fragments into spare VGPRs, take the step barrier after QK and run softmax+PV after it
# baseline (speedup 1.0000x reference)
; #define NL_WAITBAR(n) do { asm volatile("s_waitcnt vmcnt(" #n ") lgkmcnt(0)" ::: "memory"); __builtin_amdgcn_s_barrier(); asm volatile("" ::: "memory"); } while (0)
; __device__ __forceinline__ void nsa_unit(int b, int g, int tq, const Args& a, LAS unsigned char* lds, int tid, int wave, int lane, int& nxt) {
;     ...
;         int kfo[4];
; #pragma unroll
;         for (int s = 0; s < 4; ++s) kfo[s] = (lane & 31) * 128 + ((((2 * s + h) ^ (lane & 7))) << 4);
;         int o0 = 0, o1 = FBUF, o2 = 2 * FBUF;
;         float cfar = tabh[127 + 64]; asm volatile("" : "+v"(cfar));
;     ...
;         NL_WAITBAR(2);
;         {
;             float m = 0.f, l = 0.f; bool first = true; f32x16 oa = {}, ob = {};
.LBB0_945:
	v_lshlrev_b32_e32 v0, 7, v84
	v_xor_b32_e32 v2, v83, v82
	v_lshl_or_b32 v183, v2, 4, v0
	v_bitop3_b32 v2, v83, v82, 2 bitop3:0x36
	v_lshl_or_b32 v184, v2, 4, v0
	v_mov_b32_e32 v2, s96
	ds_read_b32 v185, v2 offset:764
	v_bitop3_b32 v2, v83, v82, 4 bitop3:0x36
	v_lshl_or_b32 v186, v2, 4, v0
	v_bitop3_b32 v2, v83, v82, 6 bitop3:0x36
	s_waitcnt lgkmcnt(0)
	s_waitcnt vmcnt(2) lgkmcnt(0)
	s_barrier
	v_mov_b32_e32 v14, v1
	v_mov_b32_e32 v15, v1
	v_lshl_or_b32 v187, v2, 4, v0
	v_mov_b32_e32 v0, v1
	v_mov_b32_e32 v2, v1
	v_mov_b32_e32 v3, v1
	v_mov_b32_e32 v4, v1
	v_mov_b32_e32 v5, v1
	v_mov_b32_e32 v6, v1
	v_mov_b32_e32 v7, v1
	v_mov_b32_e32 v8, v1
	v_mov_b32_e32 v9, v1
	v_mov_b32_e32 v10, v1
	v_mov_b32_e32 v11, v1
	v_mov_b32_e32 v12, v1
	v_mov_b32_e32 v13, v1
	v_mov_b64_e32 v[78:79], v[14:15]
	v_mov_b64_e32 v[62:63], v[14:15]
	v_add_u32_e32 v188, 0, v128
	s_mov_b32 s50, 0
	s_movk_i32 s51, 0x4000
	s_mov_b32 s4, 0x8000
	v_mov_b32_e32 v167, 0
	s_mov_b64 s[62:63], -1
	v_mov_b64_e32 v[76:77], v[12:13]
	v_mov_b64_e32 v[74:75], v[10:11]
	v_mov_b64_e32 v[72:73], v[8:9]
	v_mov_b64_e32 v[70:71], v[6:7]
	v_mov_b64_e32 v[68:69], v[4:5]
	v_mov_b64_e32 v[66:67], v[2:3]
	v_mov_b64_e32 v[64:65], v[0:1]
	v_mov_b64_e32 v[60:61], v[12:13]
	v_mov_b64_e32 v[58:59], v[10:11]
	v_mov_b64_e32 v[56:57], v[8:9]
	v_mov_b64_e32 v[54:55], v[6:7]
	v_mov_b64_e32 v[52:53], v[4:5]
	v_mov_b64_e32 v[50:51], v[2:3]
	v_mov_b64_e32 v[48:49], v[0:1]
	v_mov_b32_e32 v0, 0
	v_readlane_b32 s98, v248, 0
	s_nop 3
	s_cmp_ge_u32 s98, 0x100
	s_cbranch_scc1 .Lstg_946

; __device__ __forceinline__ s16x4 vtr(lds_cptr p){ return __builtin_bit_cast(s16x4,__builtin_amdgcn_ds_read_tr16_b64_v4i16((__attribute__((address_space(3))) v4i16_t*)p)); }
; #define LAS __attribute__((address_space(3)))
; #define MFMA32(a, b, c) __builtin_amdgcn_mfma_f32_32x32x16_bf16((a), (b), (c), 0, 0, 0)
; __device__ __forceinline__ s16x4 vtr(LAS const unsigned char* p) { return __builtin_bit_cast(s16x4, __builtin_amdgcn_ds_read_tr16_b64_v4i16((LAS v4i16_t*)p)); }
; #define NL_WAITBAR(n) do { asm volatile("s_waitcnt vmcnt(" #n ") lgkmcnt(0)" ::: "memory"); __builtin_amdgcn_s_barrier(); asm volatile("" ::: "memory"); } while (0)
; __device__ __forceinline__ void pv_tile(f32x16& o0, f32x16& o1, LAS const unsigned char* Vt, const bf16x8 (&pf)[4], int lane) {
;     const int q = (lane & 15) >> 2, swz = ((q >> 1) & 1) * 64;
;     LAS const unsigned char* vp0 = Vt + (4 * (lane >> 5) + q) * 128 + (((16 * ((lane >> 4) & 1) + 4 * (lane & 3)) * 2) ^ swz);
;     LAS const unsigned char* vp1 = Vt + (4 * (lane >> 5) + q) * 128 + (((16 * ((lane >> 4) & 1) + 4 * (lane & 3)) * 2 + 64) ^ swz);
; #pragma unroll
;     for (int s = 0; s < 4; ++s) {
;         const s16x4 l0 = vtr(vp0 + (16 * s) * 128), h0 = vtr(vp0 + (16 * s + 8) * 128), l1 = vtr(vp1 + (16 * s) * 128), h1 = vtr(vp1 + (16 * s + 8) * 128);
;         const bf16x8 v0 = {l0[0], l0[1], l0[2], l0[3], h0[0], h0[1], h0[2], h0[3]}, v1 = {l1[0], l1[1], l1[2], l1[3], h1[0], h1[1], h1[2], h1[3]};
;         o0 = MFMA32(v0, pf[s], o0); o1 = MFMA32(v1, pf[s], o1); }
; }
; __device__ __forceinline__ void nsa_unit(int b, int g, int tq, const Args& a, LAS unsigned char* lds, int tid, int wave, int lane, int& nxt) {
;     ...
;                 NL_STEP(1, selbits);
;                 NL_WAITBAR(2);
;                 if (j1 < 0) break;
;                 j0 = j1; j1 = j2; { const int ot = o0; o0 = o1; o1 = o2; o2 = ot; }
.LBB0_987:
	v_add_u32_e32 v10, s51, v188
	v_add3_u32 v189, v10, v181, v180
	v_exp_f32_e32 v14, v128
	v_exp_f32_e32 v15, v129
	v_exp_f32_e32 v130, v130
	v_exp_f32_e32 v131, v131
	v_exp_f32_e32 v132, v132
	v_exp_f32_e32 v133, v133
	v_exp_f32_e32 v134, v134
	v_exp_f32_e32 v135, v135
	ds_read_b64_tr_b16 v[6:7], v189 offset:8192
	ds_read_b64_tr_b16 v[8:9], v189 offset:9216
	v_add_u32_e32 v192, v10, v182
	v_exp_f32_e32 v128, v112
	v_exp_f32_e32 v129, v113
	v_exp_f32_e32 v190, v114
	v_exp_f32_e32 v191, v115
	ds_read_b64_tr_b16 v[10:11], v192 offset:8192
	ds_read_b64_tr_b16 v[12:13], v192 offset:9216
	ds_read_b64_tr_b16 v[112:113], v189 offset:10240
	ds_read_b64_tr_b16 v[114:115], v189 offset:11264
	v_cvt_pk_bf16_f32 v2, v14, v15
	v_cvt_pk_bf16_f32 v3, v130, v131
	v_cvt_pk_bf16_f32 v4, v132, v133
	v_cvt_pk_bf16_f32 v5, v134, v135
	v_exp_f32_e32 v136, v136
	v_exp_f32_e32 v137, v137
	s_waitcnt lgkmcnt(4)
	v_mfma_f32_32x32x16_bf16 v[96:111], v[6:9], v[2:5], v[96:111]
	v_exp_f32_e32 v138, v138
	v_exp_f32_e32 v139, v139
	v_exp_f32_e32 v140, v140
	v_exp_f32_e32 v141, v141
	ds_read_b64_tr_b16 v[6:7], v192 offset:10240
	ds_read_b64_tr_b16 v[8:9], v192 offset:11264
	v_exp_f32_e32 v142, v142
	v_exp_f32_e32 v143, v143
	s_waitcnt lgkmcnt(4)
	v_mfma_f32_32x32x16_bf16 v[80:95], v[10:13], v[2:5], v[80:95]
	v_cvt_pk_bf16_f32 v2, v136, v137
	v_cvt_pk_bf16_f32 v3, v138, v139
	v_cvt_pk_bf16_f32 v4, v140, v141
	v_cvt_pk_bf16_f32 v5, v142, v143
	v_exp_f32_e32 v116, v116
	v_exp_f32_e32 v117, v117
	v_exp_f32_e32 v118, v118
	s_waitcnt lgkmcnt(2)
	v_mfma_f32_32x32x16_bf16 v[96:111], v[112:115], v[2:5], v[96:111]
	v_exp_f32_e32 v119, v119
	ds_read_b64_tr_b16 v[112:113], v189 offset:12288
	ds_read_b64_tr_b16 v[114:115], v189 offset:13312
	v_cvt_pk_bf16_f32 v10, v128, v129
	v_cvt_pk_bf16_f32 v11, v190, v191
	v_cvt_pk_bf16_f32 v12, v116, v117
	v_cvt_pk_bf16_f32 v13, v118, v119
	v_exp_f32_e32 v124, v124
	s_waitcnt lgkmcnt(2)
	v_mfma_f32_32x32x16_bf16 v[80:95], v[6:9], v[2:5], v[80:95]
	ds_read_b64_tr_b16 v[2:3], v192 offset:12288
	ds_read_b64_tr_b16 v[4:5], v192 offset:13312
	ds_read_b64_tr_b16 v[6:7], v189 offset:14336
	ds_read_b64_tr_b16 v[8:9], v189 offset:15360
	v_exp_f32_e32 v125, v125
	v_exp_f32_e32 v120, v120
	v_exp_f32_e32 v121, v121
	v_exp_f32_e32 v122, v122
	v_exp_f32_e32 v123, v123
	v_exp_f32_e32 v126, v126
	s_waitcnt lgkmcnt(4)
	v_mfma_f32_32x32x16_bf16 v[96:111], v[112:115], v[10:13], v[96:111]
	v_exp_f32_e32 v127, v127
	ds_read_b64_tr_b16 v[112:113], v192 offset:14336
	ds_read_b64_tr_b16 v[114:115], v192 offset:15360
	v_pk_add_f32 v[14:15], v[128:129], v[14:15]
	v_pk_add_f32 v[128:129], v[124:125], v[140:141]
	v_pk_add_f32 v[138:139], v[122:123], v[138:139]
	v_pk_add_f32 v[130:131], v[190:191], v[130:131]
	v_pk_add_f32 v[142:143], v[126:127], v[142:143]
	s_waitcnt lgkmcnt(4)
	v_mfma_f32_32x32x16_bf16 v[80:95], v[2:5], v[10:13], v[80:95]
	v_add_f32_e64 v2, v116, v132
	v_add_f32_e64 v3, v117, v133
	v_cvt_pk_bf16_f32 v4, v124, v125
	v_add_f32_e64 v10, v2, v128
	v_add_f32_e64 v11, v3, v129
	v_cvt_pk_bf16_f32 v2, v120, v121
	v_cvt_pk_bf16_f32 v3, v122, v123
	v_cvt_pk_bf16_f32 v5, v126, v127
	v_pk_add_f32 v[118:119], v[118:119], v[134:135]
	v_pk_add_f32 v[134:135], v[120:121], v[136:137]
	s_waitcnt lgkmcnt(2)
	v_mfma_f32_32x32x16_bf16 v[96:111], v[6:9], v[2:5], v[96:111]
	v_add_f32_e64 v12, v14, v134
	v_add_f32_e64 v13, v15, v135
	v_add_f32_e64 v6, v118, v142
	v_add_f32_e64 v7, v119, v143
	v_add_f32_e64 v8, v130, v138
	v_add_f32_e64 v9, v131, v139
	s_and_b32 s0, s13, s0
	v_pk_add_f32 v[6:7], v[8:9], v[6:7]
	v_pk_add_f32 v[8:9], v[12:13], v[10:11]
	s_waitcnt vmcnt(2) lgkmcnt(0)
	s_waitcnt lgkmcnt(0)
	v_mfma_f32_32x32x16_bf16 v[80:95], v[112:115], v[2:5], v[80:95]
	v_add_f32_e64 v6, v8, v6
	v_add_f32_e64 v7, v9, v7
	s_barrier
	s_and_b64 s[4:5], s[6:7], exec
	v_add_f32_e32 v6, v6, v7
	s_cselect_b32 s4, -1, s1
	v_add_f32_e32 v166, v166, v6
	s_cmp_gt_i32 s11, -1
	s_cbranch_scc0 .LBB0_884
	s_mov_b32 s1, s51
	s_mov_b32 s51, s12
	s_mov_b32 s97, s11
	s_branch .LBB0_981
.Lstg_946:
	s_mov_b32 s44, s97
	s_mov_b32 s1, s51
	s_mov_b32 s51, s4
	s_cmp_eq_u32 s39, 0
	s_mov_b64 s[4:5], -1
	s_cbranch_scc1 .Lstg_948
	s_flbit_i32_b32 s4, s39
	s_xor_b32 s97, s4, 31
	s_lshl_b32 s4, 1, s97
	s_andn2_b32 s39, s39, s4
	s_mov_b64 s[4:5], 0

; __device__ __forceinline__ s16x4 vtr(lds_cptr p){ return __builtin_bit_cast(s16x4,__builtin_amdgcn_ds_read_tr16_b64_v4i16((__attribute__((address_space(3))) v4i16_t*)p)); }
; __device__ __forceinline__ s16x4 vtr(LAS const unsigned char* p) { return __builtin_bit_cast(s16x4, __builtin_amdgcn_ds_read_tr16_b64_v4i16((LAS v4i16_t*)p)); }
; __device__ __forceinline__ void pv_tile(f32x16& o0, f32x16& o1, LAS const unsigned char* Vt, const bf16x8 (&pf)[4], int lane) {
;     ...
;     for (int s = 0; s < 4; ++s) {
;         const s16x4 l0 = vtr(vp0 + (16 * s) * 128), h0 = vtr(vp0 + (16 * s + 8) * 128), l1 = vtr(vp1 + (16 * s) * 128), h1 = vtr(vp1 + (16 * s + 8) * 128);
;         const bf16x8 v0 = {l0[0], l0[1], l0[2], l0[3], h0[0], h0[1], h0[2], h0[3]}, v1 = {l1[0], l1[1], l1[2], l1[3], h1[0], h1[1], h1[2], h1[3]};
.Lstg_965:
	v_add_u32_e32 v228, s50, v188
	v_add3_u32 v229, v228, v181, v180
	v_add_u32_e32 v249, v228, v182
	ds_read_b64_tr_b16 v[224:225], v229 offset:8192
	ds_read_b64_tr_b16 v[226:227], v229 offset:9216
	ds_read_b64_tr_b16 v[232:233], v249 offset:8192
	ds_read_b64_tr_b16 v[234:235], v249 offset:9216
	ds_read_b64_tr_b16 v[236:237], v229 offset:10240
	ds_read_b64_tr_b16 v[238:239], v229 offset:11264
	ds_read_b64_tr_b16 v[240:241], v249 offset:10240
	ds_read_b64_tr_b16 v[242:243], v249 offset:11264
	ds_read_b64_tr_b16 v[244:245], v229 offset:12288
	ds_read_b64_tr_b16 v[246:247], v229 offset:13312
	ds_read_b64_tr_b16 v[252:253], v249 offset:12288
	ds_read_b64_tr_b16 v[254:255], v249 offset:13312
	ds_read_b64_tr_b16 v[196:197], v229 offset:14336
	ds_read_b64_tr_b16 v[198:199], v229 offset:15360
	ds_read_b64_tr_b16 v[200:201], v249 offset:14336
	ds_read_b64_tr_b16 v[202:203], v249 offset:15360
	s_waitcnt vmcnt(2) lgkmcnt(0)
	s_barrier
	v_max_f32_e32 v2, v97, v97
	v_max_f32_e32 v3, v96, v96
	v_max_f32_e32 v2, v3, v2
	v_max3_f32 v3, v98, v99, v81
	v_max3_f32 v2, v2, v80, v82
	v_max3_f32 v2, v2, v83, v100
	v_max3_f32 v3, v3, v102, v103
	v_max3_f32 v2, v2, v101, v84
	v_max3_f32 v3, v3, v86, v87
	v_max3_f32 v2, v2, v85, v104
	v_max3_f32 v3, v3, v106, v107
	v_max3_f32 v2, v2, v105, v88
	v_max3_f32 v3, v3, v90, v91
	v_max3_f32 v2, v2, v89, v108
	v_max3_f32 v3, v3, v110, v111
	v_max3_f32 v2, v2, v109, v92
	v_max3_f32 v3, v3, v94, v95
	v_max3_f32 v2, v2, v93, v3
	v_mov_b32_e32 v3, v2
	s_nop 1
	v_permlane32_swap_b32_e32 v2, v3
	s_xor_b64 s[6:7], s[62:63], -1
	v_max_f32_e32 v3, v3, v3
	v_max_f32_e32 v2, v2, v2
	v_max_f32_e32 v2, v2, v3
	v_cndmask_b32_e64 v3, 0, 1, s[6:7]
	v_cmp_ne_u32_e64 s[4:5], 1, v3
	s_andn2_b64 vcc, exec, s[6:7]
	s_mov_b64 s[6:7], -1
	s_cbranch_vccnz .Lstg_968
	v_cmp_lt_f32_e32 vcc, s91, v2
	s_cbranch_vccz .Lstg_974
	s_nop 0
	v_cndmask_b32_e32 v2, 0, v2, vcc

; __device__ __forceinline__ s16x4 vtr(lds_cptr p){ return __builtin_bit_cast(s16x4,__builtin_amdgcn_ds_read_tr16_b64_v4i16((__attribute__((address_space(3))) v4i16_t*)p)); }
; #define LAS __attribute__((address_space(3)))
; #define MFMA32(a, b, c) __builtin_amdgcn_mfma_f32_32x32x16_bf16((a), (b), (c), 0, 0, 0)
; __device__ __forceinline__ s16x4 vtr(LAS const unsigned char* p) { return __builtin_bit_cast(s16x4, __builtin_amdgcn_ds_read_tr16_b64_v4i16((LAS v4i16_t*)p)); }
; template <int MODE> __device__ __forceinline__ int pop_tile(unsigned& tiles) { int j; if (MODE == 2) { j = 31 - __builtin_clz(tiles); tiles &= ~(1u << j); } else { j = __builtin_ctz(tiles); tiles &= tiles - 1u; } return j; }
; __device__ __forceinline__ void pv_tile(f32x16& o0, f32x16& o1, LAS const unsigned char* Vt, const bf16x8 (&pf)[4], int lane) {
;     const int q = (lane & 15) >> 2, swz = ((q >> 1) & 1) * 64;
;     LAS const unsigned char* vp0 = Vt + (4 * (lane >> 5) + q) * 128 + (((16 * ((lane >> 4) & 1) + 4 * (lane & 3)) * 2) ^ swz);
;     LAS const unsigned char* vp1 = Vt + (4 * (lane >> 5) + q) * 128 + (((16 * ((lane >> 4) & 1) + 4 * (lane & 3)) * 2 + 64) ^ swz);
; #pragma unroll
;     for (int s = 0; s < 4; ++s) {
;         const s16x4 l0 = vtr(vp0 + (16 * s) * 128), h0 = vtr(vp0 + (16 * s + 8) * 128), l1 = vtr(vp1 + (16 * s) * 128), h1 = vtr(vp1 + (16 * s + 8) * 128);
;         const bf16x8 v0 = {l0[0], l0[1], l0[2], l0[3], h0[0], h0[1], h0[2], h0[3]}, v1 = {l1[0], l1[1], l1[2], l1[3], h1[0], h1[1], h1[2], h1[3]};
;         o0 = MFMA32(v0, pf[s], o0); o1 = MFMA32(v1, pf[s], o1); }
; }
; __device__ __forceinline__ void nsa_unit(int b, int g, int tq, const Args& a, LAS unsigned char* lds, int tid, int wave, int lane, int& nxt) {
;     ...
;         NL_WAITBAR(2);
;         {
;             float m = 0.f, l = 0.f; bool first = true; f32x16 oa = {}, ob = {};
;             for (;;) {
;                 int j2, m2; if (wt) { j2 = pop_tile<2>(wt); m2 = 2; } else if (ut) { j2 = pop_tile<1>(ut); m2 = 1; } else { j2 = -1; m2 = 2; }
;                 NL_DMA(m2, (j2 >= 0 ? j2 : j0), o2);
;                 NL_STEP(2, 0u);
;                 NL_WAITBAR(2);
;                 j0 = j1; m0 = m1; j1 = j2; m1 = m2; { const int ot = o0; o0 = o1; o1 = o2; o2 = ot; }
;                 if (m0 != 2) break;
.Lstg_972:
	v_exp_f32_e32 v14, v96
	v_exp_f32_e32 v15, v97
	v_exp_f32_e32 v98, v98
	v_exp_f32_e32 v99, v99
	v_exp_f32_e32 v100, v100
	v_exp_f32_e32 v101, v101
	v_exp_f32_e32 v102, v102
	v_exp_f32_e32 v103, v103
	v_exp_f32_e32 v96, v80
	v_exp_f32_e32 v97, v81
	v_exp_f32_e32 v112, v82
	v_exp_f32_e32 v113, v83
	v_cvt_pk_bf16_f32 v2, v14, v15
	v_cvt_pk_bf16_f32 v3, v98, v99
	v_cvt_pk_bf16_f32 v4, v100, v101
	v_cvt_pk_bf16_f32 v5, v102, v103
	v_exp_f32_e32 v104, v104
	v_exp_f32_e32 v105, v105
	s_nop 0
	v_mfma_f32_32x32x16_bf16 v[48:63], v[224:227], v[2:5], v[48:63]
	v_exp_f32_e32 v106, v106
	v_exp_f32_e32 v107, v107
	v_exp_f32_e32 v108, v108
	v_exp_f32_e32 v109, v109
	v_exp_f32_e32 v110, v110
	v_exp_f32_e32 v111, v111
	s_nop 0
	v_mfma_f32_32x32x16_bf16 v[64:79], v[232:235], v[2:5], v[64:79]
	v_cvt_pk_bf16_f32 v2, v104, v105
	v_cvt_pk_bf16_f32 v3, v106, v107
	v_cvt_pk_bf16_f32 v4, v108, v109
	v_cvt_pk_bf16_f32 v5, v110, v111
	v_exp_f32_e32 v84, v84
	v_exp_f32_e32 v85, v85
	v_exp_f32_e32 v86, v86
	s_nop 0
	v_mfma_f32_32x32x16_bf16 v[48:63], v[236:239], v[2:5], v[48:63]
	v_exp_f32_e32 v87, v87
	v_cvt_pk_bf16_f32 v10, v96, v97
	v_cvt_pk_bf16_f32 v11, v112, v113
	v_cvt_pk_bf16_f32 v12, v84, v85
	v_cvt_pk_bf16_f32 v13, v86, v87
	v_exp_f32_e32 v92, v92
	s_nop 0
	v_mfma_f32_32x32x16_bf16 v[64:79], v[240:243], v[2:5], v[64:79]
	v_exp_f32_e32 v93, v93
	v_exp_f32_e32 v88, v88
	v_exp_f32_e32 v89, v89
	v_exp_f32_e32 v90, v90
	v_exp_f32_e32 v91, v91
	v_exp_f32_e32 v94, v94
	s_nop 0
	v_mfma_f32_32x32x16_bf16 v[48:63], v[244:247], v[10:13], v[48:63]
	v_exp_f32_e32 v95, v95
	v_pk_add_f32 v[14:15], v[96:97], v[14:15]
	v_pk_add_f32 v[96:97], v[92:93], v[108:109]
	v_pk_add_f32 v[106:107], v[90:91], v[106:107]
	v_pk_add_f32 v[98:99], v[112:113], v[98:99]
	v_pk_add_f32 v[110:111], v[94:95], v[110:111]
	s_nop 0
	v_mfma_f32_32x32x16_bf16 v[64:79], v[252:255], v[10:13], v[64:79]
	v_add_f32_e64 v2, v84, v100
	v_add_f32_e64 v3, v85, v101
	v_cvt_pk_bf16_f32 v4, v92, v93
	v_add_f32_e64 v10, v2, v96
	v_add_f32_e64 v11, v3, v97
	v_cvt_pk_bf16_f32 v2, v88, v89
	v_cvt_pk_bf16_f32 v3, v90, v91
	v_cvt_pk_bf16_f32 v5, v94, v95
	v_pk_add_f32 v[86:87], v[86:87], v[102:103]
	v_pk_add_f32 v[102:103], v[88:89], v[104:105]
	s_nop 0
	v_mfma_f32_32x32x16_bf16 v[48:63], v[196:199], v[2:5], v[48:63]
	v_add_f32_e64 v12, v14, v102
	v_add_f32_e64 v13, v15, v103
	v_add_f32_e64 v6, v86, v110
	v_add_f32_e64 v7, v87, v111
	v_add_f32_e64 v8, v98, v106
	v_add_f32_e64 v9, v99, v107
	v_pk_add_f32 v[6:7], v[8:9], v[6:7]
	v_pk_add_f32 v[8:9], v[12:13], v[10:11]
	s_nop 0
	v_mfma_f32_32x32x16_bf16 v[64:79], v[200:203], v[2:5], v[64:79]
	v_add_f32_e64 v6, v8, v6
	v_add_f32_e64 v7, v9, v7
	s_cmp_eq_u32 s54, 2
	v_add_f32_e32 v6, v6, v7
	v_add_f32_e32 v167, v167, v6
	s_mov_b64 s[62:63], 0
	s_cbranch_scc0 .Lstg_975
	s_mov_b32 s4, s50
	s_mov_b32 s50, s1
	s_mov_b32 s54, s87
	s_mov_b32 s14, s44
	s_branch .Lstg_946

; __device__ __forceinline__ s16x4 vtr(lds_cptr p){ return __builtin_bit_cast(s16x4,__builtin_amdgcn_ds_read_tr16_b64_v4i16((__attribute__((address_space(3))) v4i16_t*)p)); }
; #define LAS __attribute__((address_space(3)))
; #define MFMA32(a, b, c) __builtin_amdgcn_mfma_f32_32x32x16_bf16((a), (b), (c), 0, 0, 0)
; __device__ __forceinline__ s16x4 vtr(LAS const unsigned char* p) { return __builtin_bit_cast(s16x4, __builtin_amdgcn_ds_read_tr16_b64_v4i16((LAS v4i16_t*)p)); }
; __device__ __forceinline__ void pv_tile(f32x16& o0, f32x16& o1, LAS const unsigned char* Vt, const bf16x8 (&pf)[4], int lane) {
;     const int q = (lane & 15) >> 2, swz = ((q >> 1) & 1) * 64;
;     LAS const unsigned char* vp0 = Vt + (4 * (lane >> 5) + q) * 128 + (((16 * ((lane >> 4) & 1) + 4 * (lane & 3)) * 2) ^ swz);
;     LAS const unsigned char* vp1 = Vt + (4 * (lane >> 5) + q) * 128 + (((16 * ((lane >> 4) & 1) + 4 * (lane & 3)) * 2 + 64) ^ swz);
; #pragma unroll
;     for (int s = 0; s < 4; ++s) {
;         const s16x4 l0 = vtr(vp0 + (16 * s) * 128), h0 = vtr(vp0 + (16 * s + 8) * 128), l1 = vtr(vp1 + (16 * s) * 128), h1 = vtr(vp1 + (16 * s + 8) * 128);
;         const bf16x8 v0 = {l0[0], l0[1], l0[2], l0[3], h0[0], h0[1], h0[2], h0[3]}, v1 = {l1[0], l1[1], l1[2], l1[3], h1[0], h1[1], h1[2], h1[3]};
;         o0 = MFMA32(v0, pf[s], o0); o1 = MFMA32(v1, pf[s], o1); }
; }
.Lstg_979:
	v_add_u32_e32 v228, s1, v128
	v_add3_u32 v229, v228, v181, v180
	v_add_u32_e32 v249, v228, v182
	ds_read_b64_tr_b16 v[224:225], v229 offset:8192
	ds_read_b64_tr_b16 v[226:227], v229 offset:9216
	ds_read_b64_tr_b16 v[232:233], v249 offset:8192
	ds_read_b64_tr_b16 v[234:235], v249 offset:9216
	ds_read_b64_tr_b16 v[236:237], v229 offset:10240
	ds_read_b64_tr_b16 v[238:239], v229 offset:11264
	ds_read_b64_tr_b16 v[240:241], v249 offset:10240
	ds_read_b64_tr_b16 v[242:243], v249 offset:11264
	ds_read_b64_tr_b16 v[244:245], v229 offset:12288
	ds_read_b64_tr_b16 v[246:247], v229 offset:13312
	ds_read_b64_tr_b16 v[252:253], v249 offset:12288
	ds_read_b64_tr_b16 v[254:255], v249 offset:13312
	ds_read_b64_tr_b16 v[196:197], v229 offset:14336
	ds_read_b64_tr_b16 v[198:199], v229 offset:15360
	ds_read_b64_tr_b16 v[200:201], v249 offset:14336
	ds_read_b64_tr_b16 v[202:203], v249 offset:15360
	s_waitcnt vmcnt(2) lgkmcnt(0)
	s_barrier
	v_max_f32_e32 v0, v97, v97
	v_max_f32_e32 v2, v96, v96
	v_max_f32_e32 v0, v2, v0
	v_max3_f32 v2, v98, v99, v81
	v_max3_f32 v0, v0, v80, v82
	v_max3_f32 v0, v0, v83, v100
	v_max3_f32 v2, v2, v102, v103
	v_max3_f32 v0, v0, v101, v84
	v_max3_f32 v2, v2, v86, v87
	v_max3_f32 v0, v0, v85, v104
	v_max3_f32 v2, v2, v106, v107
	v_max3_f32 v0, v0, v105, v88
	v_max3_f32 v2, v2, v90, v91
	v_max3_f32 v0, v0, v89, v108
	v_max3_f32 v2, v2, v110, v111
	v_max3_f32 v0, v0, v109, v92
	v_max3_f32 v2, v2, v94, v95
	v_max3_f32 v0, v0, v93, v2
	v_mov_b32_e32 v2, v0
	s_nop 1
	v_permlane32_swap_b32_e32 v0, v2
	v_max_f32_e32 v2, v2, v2
	v_max_f32_e32 v0, v0, v0
	v_max_f32_e32 v0, v0, v2
	v_sub_f32_e32 v10, v82, v0
	s_add_i32 s4, s1, 0
	v_exp_f32_e32 v120, v10
	v_sub_f32_e32 v2, v90, v0
	v_sub_f32_e32 v3, v89, v0
	v_sub_f32_e32 v4, v88, v0
	v_sub_f32_e32 v5, v87, v0
	v_sub_f32_e32 v6, v86, v0
	v_sub_f32_e32 v7, v85, v0
	v_sub_f32_e32 v8, v84, v0
	v_sub_f32_e32 v9, v83, v0
	v_sub_f32_e32 v85, v103, v0
	v_sub_f32_e32 v86, v102, v0
	v_sub_f32_e32 v87, v101, v0
	v_sub_f32_e32 v88, v100, v0
	v_sub_f32_e32 v89, v99, v0
	v_sub_f32_e32 v90, v98, v0
	v_sub_f32_e32 v15, v97, v0
	v_sub_f32_e32 v14, v96, v0
	v_exp_f32_e32 v14, v14
	v_exp_f32_e32 v15, v15
	v_exp_f32_e32 v118, v90
	v_exp_f32_e32 v119, v89
	v_exp_f32_e32 v121, v9
	v_exp_f32_e32 v122, v88
	v_exp_f32_e32 v124, v8
	v_exp_f32_e32 v123, v87
	v_exp_f32_e32 v125, v7
	v_exp_f32_e32 v126, v86
	v_exp_f32_e32 v130, v6
	v_exp_f32_e32 v127, v85
	v_sub_f32_e32 v11, v81, v0
	v_sub_f32_e32 v12, v80, v0
	v_sub_f32_e32 v13, v106, v0
	v_exp_f32_e32 v116, v12
	v_exp_f32_e32 v117, v11
	v_exp_f32_e32 v136, v13
	v_sub_f32_e32 v92, v92, v0
	v_sub_f32_e32 v91, v91, v0
	v_sub_f32_e32 v80, v109, v0
	v_sub_f32_e32 v81, v108, v0
	v_sub_f32_e32 v82, v107, v0
	v_sub_f32_e32 v83, v105, v0
	v_sub_f32_e32 v84, v104, v0
	v_exp_f32_e32 v131, v5
	v_exp_f32_e32 v134, v4
	v_exp_f32_e32 v135, v3
	v_exp_f32_e32 v138, v2
	v_cvt_pk_bf16_f32 v2, v14, v15
	v_cvt_pk_bf16_f32 v3, v118, v119
	v_cvt_pk_bf16_f32 v4, v122, v123
	v_cvt_pk_bf16_f32 v5, v126, v127
	v_sub_f32_e32 v166, v95, v0
	v_sub_f32_e32 v189, v94, v0
	v_sub_f32_e32 v141, v93, v0
	v_sub_f32_e32 v143, v111, v0
	v_sub_f32_e32 v142, v110, v0
	v_exp_f32_e32 v132, v84
	v_exp_f32_e32 v133, v83
	s_nop 0
	v_mfma_f32_32x32x16_bf16 v[96:111], v[224:227], v[2:5], 0
	v_exp_f32_e32 v137, v82
	v_exp_f32_e32 v139, v91
	v_exp_f32_e32 v128, v81
	v_exp_f32_e32 v140, v92
	v_exp_f32_e32 v129, v80
	v_exp_f32_e32 v142, v142
	s_nop 0
	v_mfma_f32_32x32x16_bf16 v[80:95], v[232:235], v[2:5], 0
	v_exp_f32_e32 v143, v143
	v_cvt_pk_bf16_f32 v2, v132, v133
	v_cvt_pk_bf16_f32 v3, v136, v137
	v_cvt_pk_bf16_f32 v4, v128, v129
	v_cvt_pk_bf16_f32 v5, v142, v143
	v_cvt_pk_bf16_f32 v10, v116, v117
	v_cvt_pk_bf16_f32 v11, v120, v121
	s_nop 0
	v_mfma_f32_32x32x16_bf16 v[96:111], v[236:239], v[2:5], v[96:111]
	v_cvt_pk_bf16_f32 v12, v124, v125
	v_cvt_pk_bf16_f32 v13, v130, v131
	v_exp_f32_e32 v141, v141
	v_exp_f32_e32 v190, v189
	v_exp_f32_e32 v191, v166
	v_pk_add_f32 v[14:15], v[116:117], v[14:15]
	s_nop 0
	v_mfma_f32_32x32x16_bf16 v[80:95], v[240:243], v[2:5], v[80:95]
	v_add_f32_e64 v116, v140, v128
	v_add_f32_e64 v117, v141, v129
	v_pk_add_f32 v[136:137], v[138:139], v[136:137]
	v_pk_add_f32 v[118:119], v[120:121], v[118:119]
	v_pk_add_f32 v[120:121], v[190:191], v[142:143]
	v_pk_add_f32 v[126:127], v[130:131], v[126:127]
	v_pk_add_f32 v[130:131], v[134:135], v[132:133]
	s_nop 0
	v_mfma_f32_32x32x16_bf16 v[96:111], v[244:247], v[10:13], v[96:111]
	s_andn2_b64 vcc, exec, s[60:61]
	s_nop 0
	v_mfma_f32_32x32x16_bf16 v[80:95], v[252:255], v[10:13], v[80:95]
	v_add_f32_e64 v2, v124, v122
	v_add_f32_e64 v3, v125, v123
	v_cvt_pk_bf16_f32 v4, v140, v141
	v_add_f32_e64 v10, v2, v116
	v_add_f32_e64 v11, v3, v117
	v_cvt_pk_bf16_f32 v2, v134, v135
	v_cvt_pk_bf16_f32 v3, v138, v139
	v_cvt_pk_bf16_f32 v5, v190, v191
	v_pk_add_f32 v[12:13], v[14:15], v[130:131]
	s_nop 0
	v_mfma_f32_32x32x16_bf16 v[96:111], v[196:199], v[2:5], v[96:111]
	v_add_f32_e64 v6, v126, v120
	v_add_f32_e64 v7, v127, v121
	v_add_f32_e64 v8, v118, v136
	v_add_f32_e64 v9, v119, v137
	v_add_f32_e64 v6, v8, v6
	v_add_f32_e64 v7, v9, v7
	v_pk_add_f32 v[8:9], v[12:13], v[10:11]
	s_nop 0
	v_pk_add_f32 v[6:7], v[8:9], v[6:7]
	s_nop 0
	v_mfma_f32_32x32x16_bf16 v[80:95], v[200:203], v[2:5], v[80:95]
	v_add_f32_e32 v6, v6, v7
	v_add_f32_e32 v166, 0, v6
	s_cbranch_vccnz .LBB0_884
	s_and_b32 s0, s12, s0
	s_and_b64 s[4:5], s[6:7], exec
	s_cselect_b32 s4, -1, s11
	v_add_f32_e32 v0, 0, v0

; template <int MODE> __device__ __forceinline__ int pop_tile(unsigned& tiles) { int j; if (MODE == 2) { j = 31 - __builtin_clz(tiles); tiles &= ~(1u << j); } else { j = __builtin_ctz(tiles); tiles &= tiles - 1u; } return j; }
; #define NL_WAITBAR(n) do { asm volatile("s_waitcnt vmcnt(" #n ") lgkmcnt(0)" ::: "memory"); __builtin_amdgcn_s_barrier(); asm volatile("" ::: "memory"); } while (0)
; __device__ __forceinline__ void nsa_unit(int b, int g, int tq, const Args& a, LAS unsigned char* lds, int tid, int wave, int lane, int& nxt) {
;     ...
;             for (;;) {
;                 const int j2 = ut ? pop_tile<1>(ut) : -1;
;                 NL_DMA(1, (j2 >= 0 ? j2 : j0), o2);
;                 NL_STEP(1, selbits);
;                 NL_WAITBAR(2);
;                 if (j1 < 0) break;
;                 j0 = j1; j1 = j2; { const int ot = o0; o0 = o1; o1 = o2; o2 = ot; }
;             }
.Lstg_985:
	v_add_u32_e32 v228, s51, v188
	v_add3_u32 v229, v228, v181, v180
	v_add_u32_e32 v249, v228, v182
	ds_read_b64_tr_b16 v[224:225], v229 offset:8192
	ds_read_b64_tr_b16 v[226:227], v229 offset:9216
	ds_read_b64_tr_b16 v[232:233], v249 offset:8192
	ds_read_b64_tr_b16 v[234:235], v249 offset:9216
	ds_read_b64_tr_b16 v[236:237], v229 offset:10240
	ds_read_b64_tr_b16 v[238:239], v229 offset:11264
	ds_read_b64_tr_b16 v[240:241], v249 offset:10240
	ds_read_b64_tr_b16 v[242:243], v249 offset:11264
	ds_read_b64_tr_b16 v[244:245], v229 offset:12288
	ds_read_b64_tr_b16 v[246:247], v229 offset:13312
	ds_read_b64_tr_b16 v[252:253], v249 offset:12288
	ds_read_b64_tr_b16 v[254:255], v249 offset:13312
	ds_read_b64_tr_b16 v[196:197], v229 offset:14336
	ds_read_b64_tr_b16 v[198:199], v229 offset:15360
	ds_read_b64_tr_b16 v[200:201], v249 offset:14336
	ds_read_b64_tr_b16 v[202:203], v249 offset:15360
	s_waitcnt vmcnt(2) lgkmcnt(0)
	s_barrier
	v_max_f32_e32 v2, v129, v129
	v_max_f32_e32 v3, v128, v128
	v_max_f32_e32 v2, v3, v2
	v_max3_f32 v3, v130, v131, v113
	v_max3_f32 v2, v2, v112, v114
	v_max3_f32 v2, v2, v115, v132
	v_max3_f32 v3, v3, v134, v135
	v_max3_f32 v2, v2, v133, v116
	v_max3_f32 v3, v3, v118, v119
	v_max3_f32 v2, v2, v117, v136
	v_max3_f32 v3, v3, v138, v139
	v_max3_f32 v2, v2, v137, v120
	v_max3_f32 v3, v3, v122, v123
	v_max3_f32 v2, v2, v121, v140
	v_max3_f32 v3, v3, v142, v143
	v_max3_f32 v2, v2, v141, v124
	v_max3_f32 v3, v3, v126, v127
	v_max3_f32 v2, v2, v125, v3
	v_mov_b32_e32 v3, v2
	s_nop 1
	v_permlane32_swap_b32_e32 v2, v3
	v_max_f32_e32 v3, v3, v3
	v_max_f32_e32 v2, v2, v2
	v_max_f32_e32 v2, v2, v3
	v_cmp_lt_f32_e32 vcc, s91, v2
	s_cbranch_vccz .Lstg_987
	s_nop 0
	v_cndmask_b32_e32 v3, 0, v2, vcc
	v_exp_f32_e64 v2, -v3
	v_sub_f32_e32 v127, v127, v3
	v_sub_f32_e32 v126, v126, v3
	v_sub_f32_e32 v125, v125, v3
	v_sub_f32_e32 v124, v124, v3
	v_sub_f32_e32 v123, v123, v3
	v_sub_f32_e32 v122, v122, v3
	v_sub_f32_e32 v121, v121, v3
	v_sub_f32_e32 v120, v120, v3
	v_sub_f32_e32 v119, v119, v3
	v_sub_f32_e32 v118, v118, v3
	v_sub_f32_e32 v117, v117, v3
	v_sub_f32_e32 v116, v116, v3
	v_sub_f32_e32 v115, v115, v3
	v_sub_f32_e32 v114, v114, v3
	v_sub_f32_e32 v113, v113, v3
	v_sub_f32_e32 v112, v112, v3
	v_sub_f32_e32 v143, v143, v3
	v_sub_f32_e32 v142, v142, v3
	v_sub_f32_e32 v141, v141, v3
	v_sub_f32_e32 v140, v140, v3
	v_sub_f32_e32 v139, v139, v3
	v_sub_f32_e32 v138, v138, v3
	v_sub_f32_e32 v137, v137, v3
	v_sub_f32_e32 v136, v136, v3
	v_sub_f32_e32 v135, v135, v3
	v_sub_f32_e32 v134, v134, v3
	v_sub_f32_e32 v133, v133, v3
	v_sub_f32_e32 v132, v132, v3
	v_sub_f32_e32 v131, v131, v3
	v_sub_f32_e32 v130, v130, v3
	v_sub_f32_e32 v129, v129, v3
	v_sub_f32_e32 v128, v128, v3
	v_add_f32_e32 v0, v0, v3
	v_mul_f32_e32 v166, v166, v2
	v_pk_mul_f32 v[110:111], v[110:111], v[2:3] op_sel_hi:[1,0]
	v_pk_mul_f32 v[108:109], v[108:109], v[2:3] op_sel_hi:[1,0]
	v_pk_mul_f32 v[106:107], v[106:107], v[2:3] op_sel_hi:[1,0]
	v_pk_mul_f32 v[104:105], v[104:105], v[2:3] op_sel_hi:[1,0]
	v_pk_mul_f32 v[102:103], v[102:103], v[2:3] op_sel_hi:[1,0]
	v_pk_mul_f32 v[100:101], v[100:101], v[2:3] op_sel_hi:[1,0]
	v_pk_mul_f32 v[98:99], v[98:99], v[2:3] op_sel_hi:[1,0]
	v_pk_mul_f32 v[96:97], v[96:97], v[2:3] op_sel_hi:[1,0]
	v_pk_mul_f32 v[94:95], v[94:95], v[2:3] op_sel_hi:[1,0]
	v_pk_mul_f32 v[92:93], v[92:93], v[2:3] op_sel_hi:[1,0]
	v_pk_mul_f32 v[90:91], v[90:91], v[2:3] op_sel_hi:[1,0]
	v_pk_mul_f32 v[88:89], v[88:89], v[2:3] op_sel_hi:[1,0]
	v_pk_mul_f32 v[86:87], v[86:87], v[2:3] op_sel_hi:[1,0]
	v_pk_mul_f32 v[84:85], v[84:85], v[2:3] op_sel_hi:[1,0]
	v_pk_mul_f32 v[82:83], v[82:83], v[2:3] op_sel_hi:[1,0]
	v_pk_mul_f32 v[80:81], v[80:81], v[2:3] op_sel_hi:[1,0]
.Lstg_987:
	v_exp_f32_e32 v14, v128
	v_exp_f32_e32 v15, v129
	v_exp_f32_e32 v130, v130
	v_exp_f32_e32 v131, v131
	v_exp_f32_e32 v132, v132
	v_exp_f32_e32 v133, v133
	v_exp_f32_e32 v134, v134
	v_exp_f32_e32 v135, v135
	v_exp_f32_e32 v128, v112
	v_exp_f32_e32 v129, v113
	v_exp_f32_e32 v190, v114
	v_exp_f32_e32 v191, v115
	v_cvt_pk_bf16_f32 v2, v14, v15
	v_cvt_pk_bf16_f32 v3, v130, v131
	v_cvt_pk_bf16_f32 v4, v132, v133
	v_cvt_pk_bf16_f32 v5, v134, v135
	v_exp_f32_e32 v136, v136
	v_exp_f32_e32 v137, v137
	s_nop 0
	v_mfma_f32_32x32x16_bf16 v[96:111], v[224:227], v[2:5], v[96:111]
	v_exp_f32_e32 v138, v138
	v_exp_f32_e32 v139, v139
	v_exp_f32_e32 v140, v140
	v_exp_f32_e32 v141, v141
	v_exp_f32_e32 v142, v142
	v_exp_f32_e32 v143, v143
	s_nop 0
	v_mfma_f32_32x32x16_bf16 v[80:95], v[232:235], v[2:5], v[80:95]
	v_cvt_pk_bf16_f32 v2, v136, v137
	v_cvt_pk_bf16_f32 v3, v138, v139
	v_cvt_pk_bf16_f32 v4, v140, v141
	v_cvt_pk_bf16_f32 v5, v142, v143
	v_exp_f32_e32 v116, v116
	v_exp_f32_e32 v117, v117
	v_exp_f32_e32 v118, v118
	s_nop 0
	v_mfma_f32_32x32x16_bf16 v[96:111], v[236:239], v[2:5], v[96:111]
	v_exp_f32_e32 v119, v119
	v_cvt_pk_bf16_f32 v10, v128, v129
	v_cvt_pk_bf16_f32 v11, v190, v191
	v_cvt_pk_bf16_f32 v12, v116, v117
	v_cvt_pk_bf16_f32 v13, v118, v119
	v_exp_f32_e32 v124, v124
	s_nop 0
	v_mfma_f32_32x32x16_bf16 v[80:95], v[240:243], v[2:5], v[80:95]
	v_exp_f32_e32 v125, v125
	v_exp_f32_e32 v120, v120
	v_exp_f32_e32 v121, v121
	v_exp_f32_e32 v122, v122
	v_exp_f32_e32 v123, v123
	v_exp_f32_e32 v126, v126
	s_nop 0
	v_mfma_f32_32x32x16_bf16 v[96:111], v[244:247], v[10:13], v[96:111]
	v_exp_f32_e32 v127, v127
	v_pk_add_f32 v[14:15], v[128:129], v[14:15]
	v_pk_add_f32 v[128:129], v[124:125], v[140:141]
	v_pk_add_f32 v[138:139], v[122:123], v[138:139]
	v_pk_add_f32 v[130:131], v[190:191], v[130:131]
	v_pk_add_f32 v[142:143], v[126:127], v[142:143]
	s_nop 0
	v_mfma_f32_32x32x16_bf16 v[80:95], v[252:255], v[10:13], v[80:95]
	v_add_f32_e64 v2, v116, v132
	v_add_f32_e64 v3, v117, v133
	v_cvt_pk_bf16_f32 v4, v124, v125
	v_add_f32_e64 v10, v2, v128
	v_add_f32_e64 v11, v3, v129
	v_cvt_pk_bf16_f32 v2, v120, v121
	v_cvt_pk_bf16_f32 v3, v122, v123
	v_cvt_pk_bf16_f32 v5, v126, v127
	v_pk_add_f32 v[118:119], v[118:119], v[134:135]
	v_pk_add_f32 v[134:135], v[120:121], v[136:137]
	s_nop 0
	v_mfma_f32_32x32x16_bf16 v[96:111], v[196:199], v[2:5], v[96:111]
	v_add_f32_e64 v12, v14, v134
	v_add_f32_e64 v13, v15, v135
	v_add_f32_e64 v6, v118, v142
	v_add_f32_e64 v7, v119, v143
	v_add_f32_e64 v8, v130, v138
	v_add_f32_e64 v9, v131, v139
	s_and_b32 s0, s13, s0
	v_pk_add_f32 v[6:7], v[8:9], v[6:7]
	v_pk_add_f32 v[8:9], v[12:13], v[10:11]
	s_nop 0
	v_mfma_f32_32x32x16_bf16 v[80:95], v[200:203], v[2:5], v[80:95]
	v_add_f32_e64 v6, v8, v6
	v_add_f32_e64 v7, v9, v7
	s_and_b64 s[4:5], s[6:7], exec
	v_add_f32_e32 v6, v6, v7
	s_cselect_b32 s4, -1, s1
	v_add_f32_e32 v166, v166, v6
	s_cmp_gt_i32 s11, -1
	s_cbranch_scc0 .LBB0_884
	s_mov_b32 s1, s51
	s_mov_b32 s51, s12
	s_mov_b32 s97, s11
	s_branch .Lstg_981

; __global__ void __launch_bounds__(NTHREADS, 2) fwd_kernel(Args a) {
	.amdhsa_kernel _Z10fwd_kernel4Args
		.amdhsa_group_segment_fixed_size 0
		.amdhsa_private_segment_fixed_size 0
		.amdhsa_kernarg_size 472
		.amdhsa_user_sgpr_count 2
		.amdhsa_user_sgpr_dispatch_ptr 0
		.amdhsa_user_sgpr_queue_ptr 0
		.amdhsa_user_sgpr_kernarg_segment_ptr 1
		.amdhsa_user_sgpr_dispatch_id 0
		.amdhsa_user_sgpr_kernarg_preload_length 0
		.amdhsa_user_sgpr_kernarg_preload_offset 0
		.amdhsa_user_sgpr_private_segment_size 0
		.amdhsa_uses_dynamic_stack 0
		.amdhsa_enable_private_segment 0
		.amdhsa_system_sgpr_workgroup_id_x 1
		.amdhsa_system_sgpr_workgroup_id_y 0
		.amdhsa_system_sgpr_workgroup_id_z 0
		.amdhsa_system_sgpr_workgroup_info 0
		.amdhsa_system_vgpr_workitem_id 0
		.amdhsa_next_free_vgpr 256
		.amdhsa_next_free_sgpr 102
		.amdhsa_accum_offset 256
		.amdhsa_reserve_vcc 1
		.amdhsa_float_round_mode_32 0
		.amdhsa_float_round_mode_16_64 0
		.amdhsa_float_denorm_mode_32 3
		.amdhsa_float_denorm_mode_16_64 3
		.amdhsa_dx10_clamp 1
		.amdhsa_ieee_mode 1
		.amdhsa_fp16_overflow 0
		.amdhsa_tg_split 0
		.amdhsa_exception_fp_ieee_invalid_op 0
		.amdhsa_exception_fp_denorm_src 0
		.amdhsa_exception_fp_ieee_div_zero 0
		.amdhsa_exception_fp_ieee_overflow 0
		.amdhsa_exception_fp_ieee_underflow 0
		.amdhsa_exception_fp_ieee_inexact 0
		.amdhsa_exception_int_div_zero 0
	.end_amdhsa_kernel

; __global__ void __launch_bounds__(NTHREADS, 2) fwd_kernel(Args a) {
.Lfunc_end0:
	.size	_Z10fwd_kernel4Args, .Lfunc_end0-_Z10fwd_kernel4Args
	.set _Z10fwd_kernel4Args.num_vgpr, 256
	.set _Z10fwd_kernel4Args.num_agpr, 0
	.set _Z10fwd_kernel4Args.numbered_sgpr, 102
	.set _Z10fwd_kernel4Args.num_named_barrier, 0
	.set _Z10fwd_kernel4Args.private_seg_size, 0
	.set _Z10fwd_kernel4Args.uses_vcc, 1
	.set _Z10fwd_kernel4Args.uses_flat_scratch, 0
	.set _Z10fwd_kernel4Args.has_dyn_sized_stack, 0
	.set _Z10fwd_kernel4Args.has_recursion, 0
	.set _Z10fwd_kernel4Args.has_indirect_call, 0

; __global__ void __launch_bounds__(NTHREADS, 2) fwd_kernel(Args a) {
amdhsa.kernels:
  - .agpr_count:     0
    .args:
      - .offset:         0
        .size:           216
        .value_kind:     by_value
      - .offset:         216
        .size:           4
        .value_kind:     hidden_block_count_x
      - .offset:         220
        .size:           4
        .value_kind:     hidden_block_count_y
      - .offset:         224
        .size:           4
        .value_kind:     hidden_block_count_z
      - .offset:         228
        .size:           2
        .value_kind:     hidden_group_size_x
      - .offset:         230
        .size:           2
        .value_kind:     hidden_group_size_y
      - .offset:         232
        .size:           2
        .value_kind:     hidden_group_size_z
      - .offset:         234
        .size:           2
        .value_kind:     hidden_remainder_x
      - .offset:         236
        .size:           2
        .value_kind:     hidden_remainder_y
      - .offset:         238
        .size:           2
        .value_kind:     hidden_remainder_z
      - .offset:         256
        .size:           8
        .value_kind:     hidden_global_offset_x
      - .offset:         264
        .size:           8
        .value_kind:     hidden_global_offset_y
      - .offset:         272
        .size:           8
        .value_kind:     hidden_global_offset_z
      - .offset:         280
        .size:           2
        .value_kind:     hidden_grid_dims
      - .offset:         336
        .size:           4
        .value_kind:     hidden_dynamic_lds_size
    .group_segment_fixed_size: 0
    .kernarg_segment_align: 8
    .kernarg_segment_size: 472
    .language:       OpenCL C
    .language_version:
      - 2
      - 0
    .max_flat_workgroup_size: 512
    .name:           _Z10fwd_kernel4Args
    .private_segment_fixed_size: 0
    .sgpr_count:     108
    .sgpr_spill_count: 9
    .symbol:         _Z10fwd_kernel4Args.kd
    .uniform_work_group_size: 1
    .uses_dynamic_stack: false
    .vgpr_count:     256
    .vgpr_spill_count: 0
    .wavefront_size: 64
